# v45 with deferred-weight split 0/0/4/7 (w_in split 0/2/3/3, P0 LDS swizzle)
# baseline (speedup 1.0000x reference)
.LBB0_155:
	s_or_b64 exec, exec, s[0:1]
	s_mov_b32 s100, 1
	s_lshr_b32 s0, s83, 6
	s_and_b32 s1, s83, 63
	s_movk_i32 s4, 0
	s_movk_i32 s5, 512
	s_cmp_eq_u32 s0, 1
	s_cselect_b32 s4, 0, s4
	s_cselect_b32 s5, 512, s5
	s_cmp_eq_u32 s0, 2
	s_cselect_b32 s4, 4, s4
	s_cselect_b32 s5, 512, s5
	s_cmp_eq_u32 s0, 3
	s_cselect_b32 s4, 7, s4
	s_cselect_b32 s5, 768, s5
	s_mul_i32 s6, s1, s4
	s_add_i32 s8, s5, s6
	s_add_i32 s10, s8, s4
	s_cmp_eq_u32 s4, 0
	s_cbranch_scc1 .Lp0_second_done
	s_mul_i32 s3, s62, 0x2080
	s_mov_b32 s33, s3
	s_branch .LBB0_34
